# scan: conflict-free swizzled row-major slot images (AT/RT/BB/KB), permuted state tiles
# speedup vs baseline: 1.0512x; 1.0195x over previous
; #define LAS __attribute__((address_space(3)))
; __device__ __forceinline__ float bf2f(bf16_t b) { return __uint_as_float(((unsigned)b) << 16); }
; __device__ __forceinline__ bf16_t bf1(float x) { return (bf16_t)(pk_bf16(x, 0.f) & 0xffffu); }
; __device__ __forceinline__ void phase_scan2(const Params& p, int l, LAS unsigned char* lds) {
;     ...
;         const float kkc = k_k[h * 64 + j], kac = k_a[h * 64 + j], rkc = r_k[h * 64 + j];
;         unsigned short kraw[16], araw[16], rraw[16]; _Float16 eraw[16]; unsigned short vraw[4];
; #pragma unroll
;         for (int t = 0; t < 16; ++t) { kraw[t] = 0; araw[t] = 0; rraw[t] = 0; eraw[t] = (_Float16)0; }
; #pragma unroll
;         for (int q = 0; q < 4; ++q) vraw[q] = 0;
;         auto pload = [&](int c) {
;             const size_t base = (tok0 + (size_t)c * 16) * 512 + h * 64;
; #pragma unroll
;             for (int t = 0; t < 16; ++t) { const size_t off = base + (size_t)t * 512 + j; kraw[t] = Kb[off]; araw[t] = Ab[off]; rraw[t] = Rb[off]; eraw[t] = EW[off]; }
; #pragma unroll
;             for (int q = 0; q < 4; ++q) vraw[q] = Vb[base + (size_t)(4 * fq + q) * 512 + rg * 16 + fr];
;         };
;         auto pbuild = [&](int c, LAS unsigned char* sl, LAS unsigned char* sc, int cnext) {
;             float W = 1.f;
;             const int m = j >> 5, tp = (j >> 4) & 1, jw = j & 15, pidx = (jw >> 2) * 8 + tp * 4 + (jw & 3);
; #pragma unroll
;             for (int t = 0; t < 16; ++t) {
;                 const float k = bf2f(kraw[t]), a = bf2f(araw[t]), r = bf2f(rraw[t]);
;                 const float q = k * kkc, kp1 = k * (1.f + (a - 1.f) * kac);
;                 *(LAS bf16_t*)(sc + 0 + (t * 64 + j) * 2) = bf1(q * q);
;                 *(LAS bf16_t*)(sc + 2048 + (t * 64 + j) * 2) = bf1(r * kp1 * rkc);
;             }
.Lsc_producer:
	s_sub_u32 s55, s25, 1
	s_cmp_gt_u32 s25, 4
	s_cselect_b32 s0, 1, 0
	s_sub_u32 s55, s55, s0
	v_mov_b32_e32 v22, 1.0
	v_mov_b32_e32 v23, 1.0
	v_mov_b32_e32 v24, 0xbfb8aa3b
	v_mov_b32_e32 v25, 0xbfb8aa3b
	v_mov_b32_e32 v28, 0x3f803f80
	v_mov_b32_e32 v29, 0x3f803f80
	v_mov_b32_e32 v30, 0x3f803f80
	v_mov_b32_e32 v31, 0x3f803f80
	v_cmp_eq_u32_e32 vcc, 0, v1
	s_nop 1
	v_cndmask_b32_e64 v21, 0, 1.0, vcc
	v_lshl_add_u32 v4, v2, 2, 0
	v_cmp_eq_u32_e32 vcc, v4, v1
	s_nop 1
	v_cndmask_b32_e64 v26, 0, 1.0, vcc
	v_cmp_gt_u32_e32 vcc, v4, v1
	s_nop 1
	v_cndmask_b32_e64 v34, 0, 1.0, vcc
	v_cmp_ge_u32_e32 vcc, v4, v1
	s_nop 1
	v_cndmask_b32_e64 v38, 0, 1.0, vcc
	v_lshl_add_u32 v4, v2, 2, 1
	v_cmp_eq_u32_e32 vcc, v4, v1
	s_nop 1
	v_cndmask_b32_e64 v27, 0, 1.0, vcc
	v_cmp_gt_u32_e32 vcc, v4, v1
	s_nop 1
	v_cndmask_b32_e64 v35, 0, 1.0, vcc
	v_cmp_ge_u32_e32 vcc, v4, v1
	s_nop 1
	v_cndmask_b32_e64 v39, 0, 1.0, vcc
	v_lshl_add_u32 v4, v2, 2, 2
	v_cmp_eq_u32_e32 vcc, v4, v1
	s_nop 1
	v_cndmask_b32_e64 v32, 0, 1.0, vcc
	v_cmp_gt_u32_e32 vcc, v4, v1
	s_nop 1
	v_cndmask_b32_e64 v36, 0, 1.0, vcc
	v_cmp_ge_u32_e32 vcc, v4, v1
	s_nop 1
	v_cndmask_b32_e64 v40, 0, 1.0, vcc
	v_lshl_add_u32 v4, v2, 2, 3
	v_cmp_eq_u32_e32 vcc, v4, v1
	s_nop 1
	v_cndmask_b32_e64 v33, 0, 1.0, vcc
	v_cmp_gt_u32_e32 vcc, v4, v1
	s_nop 1
	v_cndmask_b32_e64 v37, 0, 1.0, vcc
	v_cmp_ge_u32_e32 vcc, v4, v1
	s_nop 1
	v_cndmask_b32_e64 v41, 0, 1.0, vcc
	s_lshl_b32 s0, s52, 8
	v_lshl_add_u32 v4, v0, 2, s0
	v_readlane_b32 s14, v243, 51
	v_readlane_b32 s15, v243, 52
	s_nop 0
	s_lshl_b64 s[14:15], s[14:15], 2
	v_readlane_b32 s0, v252, 36
	v_readlane_b32 s1, v252, 37
	s_add_u32 s0, s0, s14
	s_addc_u32 s1, s1, s15
	global_load_dword v76, v4, s[0:1]
	v_readlane_b32 s0, v252, 38
	v_readlane_b32 s1, v252, 39
	s_add_u32 s0, s0, s14
	s_addc_u32 s1, s1, s15
	global_load_dword v80, v4, s[0:1]
	v_readlane_b32 s0, v252, 40
	v_readlane_b32 s1, v252, 41
	s_add_u32 s0, s0, s14
	s_addc_u32 s1, s1, s15
	global_load_dword v248, v4, s[0:1]
	s_mul_i32 s0, s54, 4096
	s_lshl_b32 s1, s55, 4
	s_add_u32 s1, s1, s0
	v_add_u32_e32 v8, s1, v1
	v_lshlrev_b32_e32 v8, 10, v8
	s_lshl_b32 s14, s52, 7
	v_lshl_add_u32 v4, v2, 5, s14
	v_add_u32_e32 v8, v8, v4
	v_lshl_add_u32 v9, v2, 2, s1
	v_lshlrev_b32_e32 v9, 10, v9
	s_lshl_b32 s15, s53, 5
	s_add_u32 s14, s14, s15
	v_lshl_add_u32 v4, v1, 1, s14
	v_add_u32_e32 v9, v9, v4
	v_lshlrev_b32_e32 v10, 5, v1
	v_lshlrev_b32_e32 v4, 1, v2
	v_and_b32_e32 v5, 7, v1
	v_xor_b32_e32 v4, v4, v5
	v_lshlrev_b32_e32 v4, 4, v4
	v_lshl_add_u32 v11, v1, 7, v4
	v_xor_b32_e32 v13, 16, v11
	v_lshlrev_b32_e32 v16, 6, v2
	v_add_u32_e32 v16, 10752, v16
	s_mul_i32 s0, s55, 2816
	s_add_u32 s0, s0, 132096
	v_add_u32_e32 v14, s0, v7
	v_add_u32_e32 v15, s0, v6
	v_lshl_add_u32 v4, v0, 2, s0
	s_waitcnt vmcnt(0)
	ds_write_b32 v4, v76 offset:2048
	ds_write_b32 v4, v80 offset:2304
	ds_write_b32 v4, v248 offset:2560
	v_lshl_add_u32 v42, v2, 6, s0
	s_mul_i32 s57, s55, 11008
	s_mov_b32 s56, 0
	s_lshl_b32 s0, s1, 5
	s_lshl_b32 s14, s52, 2
	s_add_u32 s0, s0, s14
	s_add_u32 s0, s0, 0x9000000
	s_add_u32 s50, s74, s0
	s_addc_u32 s51, s75, 0
	s_mov_b32 s58, s55
	s_mov_b32 s42, 0
	global_load_dwordx4 v[44:47], v8, s[26:27]
	global_load_dwordx4 v[48:51], v8, s[26:27] offset:16
	global_load_dwordx4 v[52:55], v8, s[36:37]
	global_load_dwordx4 v[56:59], v8, s[36:37] offset:16
	global_load_dwordx4 v[60:63], v8, s[38:39]
	global_load_dwordx4 v[64:67], v8, s[38:39] offset:16
	global_load_dwordx4 v[68:71], v8, s[46:47]
	global_load_dwordx4 v[72:75], v8, s[46:47] offset:16
	global_load_ushort v84, v9, s[60:61] offset:0
	global_load_ushort v85, v9, s[60:61] offset:1024
	global_load_ushort v86, v9, s[60:61] offset:2048
	global_load_ushort v87, v9, s[60:61] offset:3072
	v_add_u32_e32 v8, 0x18000, v8
	v_add_u32_e32 v9, 0x18000, v9
	s_nop 1

; #define LAS __attribute__((address_space(3)))
; __device__ __forceinline__ unsigned pk_bf16(float lo, float hi) { const f32x2_t f = {lo, hi}; return __builtin_bit_cast(unsigned, __builtin_convertvector(f, bf16x2_t)); }
; __device__ __forceinline__ float bf2f(bf16_t b) { return __uint_as_float(((unsigned)b) << 16); }
; __device__ __forceinline__ void phase_scan2(const Params& p, int l, LAS unsigned char* lds) {
;     ...
;             for (int t = 0; t < 16; ++t) {
;                 const float k = bf2f(kraw[t]), a = bf2f(araw[t]), r = bf2f(rraw[t]), ew = (float)eraw[t];
;                 const float kk = k * kkc * rsqrtf(fmaxf(*(LAS const float*)(sl + SC_X + t * 4), 1e-24f));
;                 const float kp = k * (1.f + (a - 1.f) * kac);
;                 const float at = -kk * W;
;                 W *= __expf(-ew);
;                 const float rt = r * W, iw = __builtin_amdgcn_rcpf(W);
;                 const unsigned wbk = pk_bf16(kk * a * iw, kp * iw), war = pk_bf16(at, rt);
;                 const bf16_t bh = (bf16_t)(wbk & 0xffffu), kh = (bf16_t)(wbk >> 16), ah = (bf16_t)(war & 0xffffu), rh = (bf16_t)(war >> 16);
;                 *(LAS bf16_t*)(sl + SC_AT + ((m * 16 + t) * 32 + pidx) * 2) = ah;
;                 *(LAS bf16_t*)(sl + SC_RT + ((m * 16 + t) * 32 + pidx) * 2) = rh;
;                 *(LAS bf16_t*)(sl + SC_BBT + (j * SC_BS + t) * 2) = bh;
;                 *(LAS bf16_t*)(sl + SC_KBT + (j * SC_BS + t) * 2) = kh;
;                 *(LAS bf16_t*)(sc + 0 + ((m * 16 + t) * 32 + pidx) * 2) = bh;
;                 *(LAS bf16_t*)(sc + 2048 + ((m * 16 + t) * 32 + pidx) * 2) = kh;
;             }
.Lsc_p_nocb:
	v_pk_mul_f32 v[88:89], v[88:89], v[176:177] op_sel_hi:[1,0]
	v_mov_b32_dpp v76, v196 row_shr:1 row_mask:0xf bank_mask:0xf bound_ctrl:1
	v_mov_b32_dpp v77, v197 row_shr:1 row_mask:0xf bank_mask:0xf bound_ctrl:1
	v_pk_mul_f32 v[80:81], v[120:121], v[196:197]
	v_pk_mul_f32 v[104:105], v[88:89], v[104:105]
	v_max_f32_e32 v76, v76, v21
	v_max_f32_e32 v77, v77, v21
	v_pk_mul_f32 v[248:249], v[104:105], v[152:153]
	v_pk_mul_f32 v[250:251], v[136:137], v[152:153]
	v_pk_mul_f32 v[76:77], v[88:89], v[76:77] neg_lo:[1,0] neg_hi:[1,0]
	v_cvt_pk_bf16_f32 v220, v80, v81
	v_cvt_pk_bf16_f32 v228, v248, v249
	v_cvt_pk_bf16_f32 v236, v250, v251
	v_cvt_pk_bf16_f32 v168, v76, v77
	v_pk_mul_f32 v[90:91], v[90:91], v[176:177] op_sel_hi:[1,0]
	v_mov_b32_dpp v76, v198 row_shr:1 row_mask:0xf bank_mask:0xf bound_ctrl:1
	v_mov_b32_dpp v77, v199 row_shr:1 row_mask:0xf bank_mask:0xf bound_ctrl:1
	v_pk_mul_f32 v[80:81], v[122:123], v[198:199]
	v_pk_mul_f32 v[106:107], v[90:91], v[106:107]
	v_max_f32_e32 v76, v76, v21
	v_max_f32_e32 v77, v77, v21
	v_pk_mul_f32 v[248:249], v[106:107], v[154:155]
	v_pk_mul_f32 v[250:251], v[138:139], v[154:155]
	v_pk_mul_f32 v[76:77], v[90:91], v[76:77] neg_lo:[1,0] neg_hi:[1,0]
	v_cvt_pk_bf16_f32 v221, v80, v81
	v_cvt_pk_bf16_f32 v229, v248, v249
	v_cvt_pk_bf16_f32 v237, v250, v251
	v_cvt_pk_bf16_f32 v169, v76, v77
	v_pk_mul_f32 v[92:93], v[92:93], v[176:177] op_sel_hi:[1,0]
	v_mov_b32_dpp v76, v200 row_shr:1 row_mask:0xf bank_mask:0xf bound_ctrl:1
	v_mov_b32_dpp v77, v201 row_shr:1 row_mask:0xf bank_mask:0xf bound_ctrl:1
	v_pk_mul_f32 v[80:81], v[124:125], v[200:201]
	v_pk_mul_f32 v[108:109], v[92:93], v[108:109]
	v_max_f32_e32 v76, v76, v21
	v_max_f32_e32 v77, v77, v21
	v_pk_mul_f32 v[248:249], v[108:109], v[156:157]
	v_pk_mul_f32 v[250:251], v[140:141], v[156:157]
	v_pk_mul_f32 v[76:77], v[92:93], v[76:77] neg_lo:[1,0] neg_hi:[1,0]
	v_cvt_pk_bf16_f32 v222, v80, v81
	v_cvt_pk_bf16_f32 v230, v248, v249
	v_cvt_pk_bf16_f32 v238, v250, v251
	v_cvt_pk_bf16_f32 v170, v76, v77
	v_pk_mul_f32 v[94:95], v[94:95], v[176:177] op_sel_hi:[1,0]
	v_mov_b32_dpp v76, v202 row_shr:1 row_mask:0xf bank_mask:0xf bound_ctrl:1
	v_mov_b32_dpp v77, v203 row_shr:1 row_mask:0xf bank_mask:0xf bound_ctrl:1
	v_pk_mul_f32 v[80:81], v[126:127], v[202:203]
	v_pk_mul_f32 v[110:111], v[94:95], v[110:111]
	v_max_f32_e32 v76, v76, v21
	v_max_f32_e32 v77, v77, v21
	v_pk_mul_f32 v[248:249], v[110:111], v[158:159]
	v_pk_mul_f32 v[250:251], v[142:143], v[158:159]
	v_pk_mul_f32 v[76:77], v[94:95], v[76:77] neg_lo:[1,0] neg_hi:[1,0]
	v_cvt_pk_bf16_f32 v223, v80, v81
	v_cvt_pk_bf16_f32 v231, v248, v249
	v_cvt_pk_bf16_f32 v239, v250, v251
	v_cvt_pk_bf16_f32 v171, v76, v77
	v_pk_mul_f32 v[96:97], v[96:97], v[176:177] op_sel_hi:[1,0]
	v_mov_b32_dpp v76, v204 row_shr:1 row_mask:0xf bank_mask:0xf bound_ctrl:1
	v_mov_b32_dpp v77, v205 row_shr:1 row_mask:0xf bank_mask:0xf bound_ctrl:1
	v_pk_mul_f32 v[80:81], v[128:129], v[204:205]
	v_pk_mul_f32 v[112:113], v[96:97], v[112:113]
	v_max_f32_e32 v76, v76, v21
	v_max_f32_e32 v77, v77, v21
	v_pk_mul_f32 v[248:249], v[112:113], v[160:161]
	v_pk_mul_f32 v[250:251], v[144:145], v[160:161]
	v_pk_mul_f32 v[76:77], v[96:97], v[76:77] neg_lo:[1,0] neg_hi:[1,0]
	v_cvt_pk_bf16_f32 v224, v80, v81
	v_cvt_pk_bf16_f32 v232, v248, v249
	v_cvt_pk_bf16_f32 v244, v250, v251
	v_cvt_pk_bf16_f32 v172, v76, v77
	v_pk_mul_f32 v[98:99], v[98:99], v[176:177] op_sel_hi:[1,0]
	v_mov_b32_dpp v76, v206 row_shr:1 row_mask:0xf bank_mask:0xf bound_ctrl:1
	v_mov_b32_dpp v77, v207 row_shr:1 row_mask:0xf bank_mask:0xf bound_ctrl:1
	v_pk_mul_f32 v[80:81], v[130:131], v[206:207]
	v_pk_mul_f32 v[114:115], v[98:99], v[114:115]
	v_max_f32_e32 v76, v76, v21
	v_max_f32_e32 v77, v77, v21
	v_pk_mul_f32 v[248:249], v[114:115], v[162:163]
	v_pk_mul_f32 v[250:251], v[146:147], v[162:163]
	v_pk_mul_f32 v[76:77], v[98:99], v[76:77] neg_lo:[1,0] neg_hi:[1,0]
	v_cvt_pk_bf16_f32 v225, v80, v81
	v_cvt_pk_bf16_f32 v233, v248, v249
	v_cvt_pk_bf16_f32 v245, v250, v251
	v_cvt_pk_bf16_f32 v173, v76, v77
	v_pk_mul_f32 v[100:101], v[100:101], v[176:177] op_sel_hi:[1,0]
	v_mov_b32_dpp v76, v208 row_shr:1 row_mask:0xf bank_mask:0xf bound_ctrl:1
	v_mov_b32_dpp v77, v209 row_shr:1 row_mask:0xf bank_mask:0xf bound_ctrl:1
	v_pk_mul_f32 v[80:81], v[132:133], v[208:209]
	v_pk_mul_f32 v[116:117], v[100:101], v[116:117]
	v_max_f32_e32 v76, v76, v21
	v_max_f32_e32 v77, v77, v21
	v_pk_mul_f32 v[248:249], v[116:117], v[164:165]
	v_pk_mul_f32 v[250:251], v[148:149], v[164:165]
	v_pk_mul_f32 v[76:77], v[100:101], v[76:77] neg_lo:[1,0] neg_hi:[1,0]
	v_cvt_pk_bf16_f32 v226, v80, v81
	v_cvt_pk_bf16_f32 v234, v248, v249
	v_cvt_pk_bf16_f32 v246, v250, v251
	v_cvt_pk_bf16_f32 v174, v76, v77
	v_pk_mul_f32 v[102:103], v[102:103], v[176:177] op_sel_hi:[1,0]
	v_mov_b32_dpp v76, v210 row_shr:1 row_mask:0xf bank_mask:0xf bound_ctrl:1
	v_mov_b32_dpp v77, v211 row_shr:1 row_mask:0xf bank_mask:0xf bound_ctrl:1
	v_pk_mul_f32 v[80:81], v[134:135], v[210:211]
	v_pk_mul_f32 v[118:119], v[102:103], v[118:119]
; __device__ __forceinline__ void phase_scan2(const Params& p, int l, LAS unsigned char* lds) {
;     ...
;                 const unsigned wbk = pk_bf16(kk * a * iw, kp * iw), war = pk_bf16(at, rt);
;                 const bf16_t bh = (bf16_t)(wbk & 0xffffu), kh = (bf16_t)(wbk >> 16), ah = (bf16_t)(war & 0xffffu), rh = (bf16_t)(war >> 16);
;                 *(LAS bf16_t*)(sl + SC_AT + ((m * 16 + t) * 32 + pidx) * 2) = ah;
;                 *(LAS bf16_t*)(sl + SC_RT + ((m * 16 + t) * 32 + pidx) * 2) = rh;
;                 *(LAS bf16_t*)(sl + SC_BBT + (j * SC_BS + t) * 2) = bh;
;                 *(LAS bf16_t*)(sl + SC_KBT + (j * SC_BS + t) * 2) = kh;
;                 *(LAS bf16_t*)(sc + 0 + ((m * 16 + t) * 32 + pidx) * 2) = bh;
;                 *(LAS bf16_t*)(sc + 2048 + ((m * 16 + t) * 32 + pidx) * 2) = kh;
;             }
;             *(LAS float*)(sl + SC_WC + j * 4) = W;
; #pragma unroll
;             for (int q = 0; q < 4; ++q) *(LAS bf16_t*)(sl + SC_VP + (fr * 16 + 4 * fq + q) * 2) = vraw[q];
;             if (cnext >= 0) pload(cnext);
;             asm volatile("s_waitcnt lgkmcnt(0)" ::: "memory");
;             f32x4 AB = (f32x4){0.f, 0.f, 0.f, 0.f}, AKm = AB, RBm = AB, RKm = AB;
; #pragma unroll
;             for (int kk2 = 0; kk2 < 2; ++kk2) {
;                 const int fo = ((kk2 * 16 + fr) * 32 + fq * 8) * 2;
;                 const bf16x8 fa = *(LAS const bf16x8*)(sl + SC_AT + fo), fr_ = *(LAS const bf16x8*)(sl + SC_RT + fo);
;                 const bf16x8 fb = *(LAS const bf16x8*)(sc + 0 + fo), fk = *(LAS const bf16x8*)(sc + 2048 + fo);
;                 AB = __builtin_amdgcn_mfma_f32_16x16x32_bf16(fa, fb, AB, 0, 0, 0); AKm = __builtin_amdgcn_mfma_f32_16x16x32_bf16(fa, fk, AKm, 0, 0, 0);
;                 RBm = __builtin_amdgcn_mfma_f32_16x16x32_bf16(fr_, fb, RBm, 0, 0, 0); RKm = __builtin_amdgcn_mfma_f32_16x16x32_bf16(fr_, fk, RKm, 0, 0, 0);
;             }
; #pragma unroll
;             for (int r = 0; r < 4; ++r) { const int t = 4 * fq + r; const bool lo = fr < t, le = fr <= t;
;                 AB[r] = lo ? AB[r] : 0.f; AKm[r] = lo ? AKm[r] : 0.f; RBm[r] = le ? RBm[r] : 0.f; RKm[r] = le ? RKm[r] : 0.f; }
;             asm volatile("s_waitcnt lgkmcnt(0)" ::: "memory");
;             st_mat(sl + SC_AK, nullptr, nullptr, nullptr, AKm, fr, fq);
;             st_mat(sl + SC_RB, nullptr, nullptr, nullptr, RBm, fr, fq);
	v_max_f32_e32 v76, v76, v21
	v_max_f32_e32 v77, v77, v21
	v_pk_mul_f32 v[248:249], v[118:119], v[166:167]
	v_pk_mul_f32 v[250:251], v[150:151], v[166:167]
	v_pk_mul_f32 v[76:77], v[102:103], v[76:77] neg_lo:[1,0] neg_hi:[1,0]
	v_cvt_pk_bf16_f32 v227, v80, v81
	v_cvt_pk_bf16_f32 v235, v248, v249
	v_cvt_pk_bf16_f32 v247, v250, v251
	v_cvt_pk_bf16_f32 v175, v76, v77
	ds_write_b128 v17, v[168:171] offset:0
	ds_write_b128 v18, v[172:175] offset:0
	ds_write_b128 v17, v[220:223] offset:2048
	ds_write_b128 v18, v[224:227] offset:2048
	ds_write_b128 v17, v[228:231] offset:4096
	ds_write_b128 v18, v[232:235] offset:4096
	ds_write_b128 v17, v[236:239] offset:6144
	ds_write_b128 v18, v[244:247] offset:6144
	s_mov_b32 exec_lo, 0x80008000
	s_mov_b32 exec_hi, 0x80008000
	ds_write_b128 v20, v[196:199] offset:0
	ds_write_b128 v20, v[200:203] offset:16
	ds_write_b128 v20, v[204:207] offset:32
	ds_write_b128 v20, v[208:211] offset:48
	s_mov_b64 exec, -1
	v_mfma_f32_16x16x32_bf16 v[88:91], v[168:171], v[228:231], 0
	v_mfma_f32_16x16x32_bf16 v[92:95], v[168:171], v[236:239], 0
	v_mfma_f32_16x16x32_bf16 v[96:99], v[220:223], v[228:231], 0
	v_mfma_f32_16x16x32_bf16 v[100:103], v[220:223], v[236:239], 0
	v_mfma_f32_16x16x32_bf16 v[88:91], v[172:175], v[232:235], v[88:91]
	v_mfma_f32_16x16x32_bf16 v[92:95], v[172:175], v[244:247], v[92:95]
	v_mfma_f32_16x16x32_bf16 v[96:99], v[224:227], v[232:235], v[96:99]
	v_mfma_f32_16x16x32_bf16 v[100:103], v[224:227], v[244:247], v[100:103]
	s_nop 4
	v_mul_f32_e32 v88, v34, v88
	v_mul_f32_e32 v89, v35, v89
	v_mul_f32_e32 v90, v36, v90
	v_mul_f32_e32 v91, v37, v91
	v_mul_f32_e32 v92, v34, v92
	v_mul_f32_e32 v93, v35, v93
	v_mul_f32_e32 v94, v36, v94
	v_mul_f32_e32 v95, v37, v95
	v_mul_f32_e32 v96, v38, v96
	v_mul_f32_e32 v97, v39, v97
	v_mul_f32_e32 v98, v40, v98
	v_mul_f32_e32 v99, v41, v99
	v_mul_f32_e32 v100, v38, v100
	v_mul_f32_e32 v101, v39, v101
	v_mul_f32_e32 v102, v40, v102
	v_mul_f32_e32 v103, v41, v103
	v_cvt_pk_bf16_f32 v76, v92, v93
	v_cvt_pk_bf16_f32 v77, v94, v95
	ds_write_b64 v19, v[76:77] offset:8192
	v_cvt_pk_bf16_f32 v76, v96, v97
	v_cvt_pk_bf16_f32 v77, v98, v99
	ds_write_b64 v19, v[76:77] offset:9216
	v_cvt_pk_bf16_f32 v76, v100, v101
	v_cvt_pk_bf16_f32 v77, v102, v103
	ds_write_b64 v19, v[76:77] offset:9728
	v_cvt_pk_bf16_f32 v76, v88, v89
	v_cvt_pk_bf16_f32 v77, v90, v91
	ds_write_b64 v15, v[76:77] offset:0
	v_add_f32_e32 v248, v26, v88
	v_add_f32_e32 v249, v27, v89
	v_add_f32_e32 v250, v32, v90
	v_add_f32_e32 v251, v33, v91
	v_cvt_pk_bf16_f32 v80, v248, v249
	v_cvt_pk_bf16_f32 v81, v250, v251
	ds_write_b64 v15, v[80:81] offset:512
	s_waitcnt lgkmcnt(0)
	ds_read_b64_tr_b16 v[112:113], v14 offset:0
	ds_read_b64 v[114:115], v15 offset:0
	s_waitcnt lgkmcnt(0)
	v_mfma_f32_16x16x16_bf16 v[104:107], v[112:113], v[114:115], 0
	s_nop 7
	v_cvt_pk_bf16_f32 v76, v104, v105
	v_cvt_pk_bf16_f32 v77, v106, v107
	ds_write_b64 v15, v[76:77] offset:1024
	v_add_f32_e32 v248, v26, v104
	v_add_f32_e32 v249, v27, v105
	v_add_f32_e32 v250, v32, v106
	v_add_f32_e32 v251, v33, v107
	v_cvt_pk_bf16_f32 v80, v248, v249
	v_cvt_pk_bf16_f32 v81, v250, v251
	ds_write_b64 v15, v[80:81] offset:1536
	s_waitcnt lgkmcnt(0)
	ds_read_b64_tr_b16 v[112:113], v14 offset:1024
	ds_read_b64 v[114:115], v15 offset:1024
	ds_read_b64_tr_b16 v[116:117], v14 offset:512
	ds_read_b64 v[118:119], v15 offset:1536
	s_waitcnt lgkmcnt(2)
	v_mfma_f32_16x16x16_bf16 v[104:107], v[112:113], v[114:115], 0
	s_waitcnt lgkmcnt(0)
	v_mfma_f32_16x16x16_bf16 v[108:111], v[116:117], v[118:119], 0
	s_nop 5
	v_cvt_pk_bf16_f32 v76, v104, v105
	v_cvt_pk_bf16_f32 v77, v106, v107
	ds_write_b64 v15, v[76:77] offset:0
	v_add_f32_e32 v248, v26, v104
	v_add_f32_e32 v249, v27, v105
	v_add_f32_e32 v250, v32, v106
	v_add_f32_e32 v251, v33, v107
	v_cvt_pk_bf16_f32 v80, v248, v249
	v_cvt_pk_bf16_f32 v81, v250, v251
	ds_write_b64 v15, v[80:81] offset:512
	v_cvt_pk_bf16_f32 v76, v108, v109
	v_cvt_pk_bf16_f32 v77, v110, v111
	ds_write_b64 v15, v[76:77] offset:1024
	s_waitcnt lgkmcnt(0)
	ds_read_b64_tr_b16 v[112:113], v14 offset:0
	ds_read_b64 v[114:115], v15 offset:0
	ds_read_b64_tr_b16 v[116:117], v14 offset:1024
	ds_read_b64 v[118:119], v15 offset:512
	s_waitcnt lgkmcnt(2)
	v_mfma_f32_16x16x16_bf16 v[104:107], v[112:113], v[114:115], 0
	s_waitcnt lgkmcnt(0)
	v_mfma_f32_16x16x16_bf16 v[108:111], v[116:117], v[118:119], 0
	s_nop 5
	v_add_f32_e32 v248, v26, v104
	v_add_f32_e32 v249, v27, v105
	v_add_f32_e32 v250, v32, v106
	v_add_f32_e32 v251, v33, v107
	v_cvt_pk_bf16_f32 v80, v248, v249
	v_cvt_pk_bf16_f32 v81, v250, v251
	ds_write_b64 v15, v[80:81] offset:1536
	v_cvt_pk_bf16_f32 v76, v108, v109
	v_cvt_pk_bf16_f32 v77, v110, v111
	ds_write_b64 v15, v[76:77] offset:0
	s_waitcnt lgkmcnt(0)
	ds_read_b64_tr_b16 v[112:113], v14 offset:0
	ds_read_b64 v[114:115], v15 offset:1536
	s_waitcnt lgkmcnt(0)
	v_mfma_f32_16x16x16_bf16 v[104:107], v[112:113], v[114:115], 0
	s_nop 7
	v_cvt_pk_bf16_f32 v76, v104, v105
	v_cvt_pk_bf16_f32 v77, v106, v107
	ds_write_b64 v19, v[76:77] offset:8704
	s_nop 0

; #define LAS __attribute__((address_space(3)))
; __device__ __forceinline__ unsigned pk_bf16(float lo, float hi) { const f32x2_t f = {lo, hi}; return __builtin_bit_cast(unsigned, __builtin_convertvector(f, bf16x2_t)); }
; __device__ __forceinline__ void phase_scan2(const Params& p, int l, LAS unsigned char* lds) {
;     ...
;         f32x4 ST[4];
; #pragma unroll
;         for (int jt = 0; jt < 4; ++jt) ST[jt] = (f32x4){0.f, 0.f, 0.f, 0.f};
;         auto consume = [&](int c, LAS const unsigned char* sl) {
;             const bf16x8 s0 = __builtin_bit_cast(bf16x8, (u32x4){pk_bf16(ST[0][0], ST[0][1]), pk_bf16(ST[0][2], ST[0][3]), pk_bf16(ST[1][0], ST[1][1]), pk_bf16(ST[1][2], ST[1][3])});
;             const bf16x8 s1 = __builtin_bit_cast(bf16x8, (u32x4){pk_bf16(ST[2][0], ST[2][1]), pk_bf16(ST[2][2], ST[2][3]), pk_bf16(ST[3][0], ST[3][1]), pk_bf16(ST[3][2], ST[3][3])});
;             const bf16x8 at0 = *(LAS const bf16x8*)(sl + SC_AT + (fr * 32 + fq * 8) * 2), at1 = *(LAS const bf16x8*)(sl + SC_AT + ((16 + fr) * 32 + fq * 8) * 2);
;             const bf16x8 rt0 = *(LAS const bf16x8*)(sl + SC_RT + (fr * 32 + fq * 8) * 2), rt1 = *(LAS const bf16x8*)(sl + SC_RT + ((16 + fr) * 32 + fq * 8) * 2);
;             const int mo = (fr * 16 + 4 * fq) * 2;
;             const bf16x8 vf = frag4(sl + SC_VP + mo), akf = frag4(sl + SC_AK + mo), xf = frag4(sl + SC_X + mo), rbf = frag4(sl + SC_RB + mo), rkf = frag4(sl + SC_RK + mo);
;             const f32x4 z = (f32x4){0.f, 0.f, 0.f, 0.f};
.Lsc_consumer:
	v_mov_b32_e32 v8, 0
	v_mov_b32_e32 v9, 0
	v_mov_b32_e32 v10, 0
	v_mov_b32_e32 v11, 0
	v_mov_b32_e32 v16, 0
	v_mov_b32_e32 v17, 0
	v_mov_b32_e32 v18, 0
	v_mov_b32_e32 v19, 0
	v_mov_b32_e32 v20, 0
	v_mov_b32_e32 v21, 0
	v_mov_b32_e32 v22, 0
	v_mov_b32_e32 v23, 0
	v_mov_b32_e32 v24, 0
	v_mov_b32_e32 v25, 0
	v_mov_b32_e32 v26, 0
	v_mov_b32_e32 v27, 0
	v_and_b32_e32 v4, 7, v1
	v_xor_b32_e32 v4, v4, v2
	v_lshlrev_b32_e32 v4, 4, v4
	v_lshl_add_u32 v113, v1, 7, v4
	v_xor_b32_e32 v119, 64, v113
	v_lshlrev_b32_e32 v114, 5, v2
	v_add_u32_e32 v114, 10752, v114
	v_lshrrev_b32_e32 v4, 2, v1
	v_lshl_add_u32 v4, v2, 2, v4
	v_and_b32_e32 v5, 3, v1
	v_and_b32_e32 v115, 7, v4
	v_xor_b32_e32 v115, v115, v5
	v_lshlrev_b32_e32 v115, 4, v115
	v_lshl_add_u32 v115, v4, 7, v115
	v_add_u32_e32 v115, 4096, v115
	v_xor_b32_e32 v120, 64, v115
	v_lshlrev_b32_e32 v116, 12, v2
	v_lshl_add_u32 v116, v1, 1, v116
	s_mul_i32 s0, s54, 4096
	s_lshl_b32 s0, s0, 10
	s_lshl_b32 s14, s52, 7
	s_lshl_b32 s15, s53, 5
	s_add_u32 s0, s0, s14
	s_add_u32 s0, s0, s15
	s_add_u32 s0, s0, 0x5000000
	s_add_u32 s48, s74, s0
	s_addc_u32 s49, s75, 0
	s_mov_b32 s42, 0
	s_mov_b32 s58, 0
	s_mov_b32 s56, 0
	s_branch .Lsc_c_bar

; __device__ __forceinline__ void phase_scan2(const Params& p, int l, LAS unsigned char* lds) {
;     ...
;         auto consume = [&](int c, LAS const unsigned char* sl) {
;             const bf16x8 s0 = __builtin_bit_cast(bf16x8, (u32x4){pk_bf16(ST[0][0], ST[0][1]), pk_bf16(ST[0][2], ST[0][3]), pk_bf16(ST[1][0], ST[1][1]), pk_bf16(ST[1][2], ST[1][3])});
;             const bf16x8 s1 = __builtin_bit_cast(bf16x8, (u32x4){pk_bf16(ST[2][0], ST[2][1]), pk_bf16(ST[2][2], ST[2][3]), pk_bf16(ST[3][0], ST[3][1]), pk_bf16(ST[3][2], ST[3][3])});
;             const bf16x8 at0 = *(LAS const bf16x8*)(sl + SC_AT + (fr * 32 + fq * 8) * 2), at1 = *(LAS const bf16x8*)(sl + SC_AT + ((16 + fr) * 32 + fq * 8) * 2);
;             const bf16x8 rt0 = *(LAS const bf16x8*)(sl + SC_RT + (fr * 32 + fq * 8) * 2), rt1 = *(LAS const bf16x8*)(sl + SC_RT + ((16 + fr) * 32 + fq * 8) * 2);
;             const int mo = (fr * 16 + 4 * fq) * 2;
;             const bf16x8 vf = frag4(sl + SC_VP + mo), akf = frag4(sl + SC_AK + mo), xf = frag4(sl + SC_X + mo), rbf = frag4(sl + SC_RB + mo), rkf = frag4(sl + SC_RK + mo);
;             const f32x4 z = (f32x4){0.f, 0.f, 0.f, 0.f};
;             f32x4 g = __builtin_amdgcn_mfma_f32_16x16x32_bf16(at0, s0, z, 0, 0, 0);
;             g = __builtin_amdgcn_mfma_f32_16x16x32_bf16(at1, s1, g, 0, 0, 0);
;             g = __builtin_amdgcn_mfma_f32_16x16x32_bf16(akf, vf, g, 0, 0, 0);
;             const f32x4 sa = __builtin_amdgcn_mfma_f32_16x16x32_bf16(xf, cfrag(g), z, 0, 0, 0);
;             const bf16x8 saf = cfrag(sa);
;             f32x4 y = __builtin_amdgcn_mfma_f32_16x16x32_bf16(rt0, s0, z, 0, 0, 0);
;             y = __builtin_amdgcn_mfma_f32_16x16x32_bf16(rt1, s1, y, 0, 0, 0);
;             y = __builtin_amdgcn_mfma_f32_16x16x32_bf16(rbf, saf, y, 0, 0, 0);
;             y = __builtin_amdgcn_mfma_f32_16x16x32_bf16(rkf, vf, y, 0, 0, 0);
; #pragma unroll
;             for (int jt = 0; jt < 4; ++jt) {
;                 const f32x4 wc = *(LAS const f32x4*)(sl + SC_WC + (16 * jt + 4 * fq) * 4);
;                 const bf16x8 bb = frag4(sl + SC_BBT + ((16 * jt + fr) * SC_BS + 4 * fq) * 2), kb = frag4(sl + SC_KBT + ((16 * jt + fr) * SC_BS + 4 * fq) * 2);
;                 f32x4 acc = ST[jt];
;                 acc = __builtin_amdgcn_mfma_f32_16x16x32_bf16(bb, saf, acc, 0, 0, 0);
;                 acc = __builtin_amdgcn_mfma_f32_16x16x32_bf16(kb, vf, acc, 0, 0, 0);
.Lsc_c_chunk:
	s_cmp_ge_u32 s58, 256
	s_cbranch_scc1 .Lsc_c_next
	v_add_u32_e32 v13, s57, v113
	v_add_u32_e32 v78, s57, v6
	v_add_u32_e32 v82, s57, v114
	v_add_u32_e32 v112, s57, v115
	v_add_u32_e32 v118, s57, v7
	v_add_u32_e32 v121, s57, v119
	v_add_u32_e32 v122, s57, v120
	ds_read_b128 v[36:39], v13 offset:0
	ds_read_b128 v[44:47], v13 offset:2048
	ds_read_b128 v[40:43], v121 offset:0
	ds_read_b128 v[48:51], v121 offset:2048
	ds_read_b64 v[14:15], v78 offset:10240
	ds_read_b64_tr_b16 v[88:89], v112 offset:2048
	ds_read_b64_tr_b16 v[90:91], v112 offset:2056
	ds_read_b64_tr_b16 v[92:93], v122 offset:2048
	ds_read_b64_tr_b16 v[94:95], v122 offset:2056
	ds_read_b64_tr_b16 v[52:53], v118 offset:8192
	ds_read_b64_tr_b16 v[58:59], v118 offset:9728
	ds_read_b64_tr_b16 v[54:55], v118 offset:8704
	ds_read_b64_tr_b16 v[56:57], v118 offset:9216
	v_cvt_pk_bf16_f32 v28, v8, v9
	v_cvt_pk_bf16_f32 v29, v10, v11
	v_cvt_pk_bf16_f32 v30, v16, v17
	v_cvt_pk_bf16_f32 v31, v18, v19
	v_cvt_pk_bf16_f32 v32, v20, v21
	v_cvt_pk_bf16_f32 v33, v22, v23
	v_cvt_pk_bf16_f32 v34, v24, v25
	v_cvt_pk_bf16_f32 v35, v26, v27
	s_waitcnt lgkmcnt(12)
	v_mfma_f32_16x16x32_bf16 v[96:99], v[36:39], v[28:31], 0
	s_waitcnt lgkmcnt(11)
	v_mfma_f32_16x16x32_bf16 v[104:107], v[44:47], v[28:31], 0
	ds_read_b64_tr_b16 v[76:77], v112 offset:0
	ds_read_b64_tr_b16 v[80:81], v112 offset:8
	ds_read_b64_tr_b16 v[84:85], v122 offset:0
	ds_read_b64_tr_b16 v[86:87], v122 offset:8
	s_waitcnt lgkmcnt(14)
	v_mfma_f32_16x16x32_bf16 v[96:99], v[40:43], v[32:35], v[96:99]
	s_waitcnt lgkmcnt(13)
	v_mfma_f32_16x16x32_bf16 v[104:107], v[48:51], v[32:35], v[104:107]
	s_waitcnt lgkmcnt(8)
	v_mfma_f32_16x16x16_bf16 v[8:11], v[88:89], v[14:15], v[8:11]
	v_mfma_f32_16x16x16_bf16 v[16:19], v[90:91], v[14:15], v[16:19]
	v_mfma_f32_16x16x16_bf16 v[20:23], v[92:93], v[14:15], v[20:23]
	v_mfma_f32_16x16x16_bf16 v[24:27], v[94:95], v[14:15], v[24:27]
	ds_read_b128 v[60:63], v82 offset:0
	ds_read_b128 v[64:67], v82 offset:16
	ds_read_b128 v[68:71], v82 offset:128
	ds_read_b128 v[72:75], v82 offset:144
	s_waitcnt lgkmcnt(10)
	v_mfma_f32_16x16x16_bf16 v[96:99], v[52:53], v[14:15], v[96:99]
	v_mfma_f32_16x16x16_bf16 v[104:107], v[58:59], v[14:15], v[104:107]
	s_nop 6
	v_cvt_pk_bf16_f32 v108, v96, v97
	v_cvt_pk_bf16_f32 v109, v98, v99
	s_waitcnt lgkmcnt(9)
	s_nop 0
	v_mfma_f32_16x16x16_bf16 v[100:103], v[54:55], v[108:109], 0
	s_nop 7
	v_cvt_pk_bf16_f32 v110, v100, v101
	v_cvt_pk_bf16_f32 v111, v102, v103
	s_waitcnt lgkmcnt(4)
	s_nop 0
	v_mfma_f32_16x16x16_bf16 v[104:107], v[56:57], v[110:111], v[104:107]
	v_mfma_f32_16x16x16_bf16 v[8:11], v[76:77], v[110:111], v[8:11]
	v_mfma_f32_16x16x16_bf16 v[16:19], v[80:81], v[110:111], v[16:19]
	v_mfma_f32_16x16x16_bf16 v[20:23], v[84:85], v[110:111], v[20:23]
	v_mfma_f32_16x16x16_bf16 v[24:27], v[86:87], v[110:111], v[24:27]
	s_nop 3
	v_cvt_pk_bf16_f32 v117, v104, v104
	global_store_short v116, v117, s[48:49] offset:0
	v_cvt_pk_bf16_f32 v117, v105, v105
	global_store_short v116, v117, s[48:49] offset:1024
	v_cvt_pk_bf16_f32 v117, v106, v106
	global_store_short v116, v117, s[48:49] offset:2048
	v_cvt_pk_bf16_f32 v117, v107, v107
	global_store_short v116, v117, s[48:49] offset:3072
	s_waitcnt lgkmcnt(0)
	v_pk_mul_f32 v[8:9], v[8:9], v[60:61]
	v_pk_mul_f32 v[10:11], v[10:11], v[62:63]
	v_pk_mul_f32 v[16:17], v[16:17], v[64:65]
	v_pk_mul_f32 v[18:19], v[18:19], v[66:67]
	v_pk_mul_f32 v[20:21], v[20:21], v[68:69]
	v_pk_mul_f32 v[22:23], v[22:23], v[70:71]
	v_pk_mul_f32 v[24:25], v[24:25], v[72:73]
	v_pk_mul_f32 v[26:27], v[26:27], v[74:75]
	s_nop 1
